# XCD census at attention start: all 16 counter loads issued together instead of one round trip each
# speedup vs baseline: 1.0111x; 1.0048x over previous
.LBB0_432:
	v_add_co_u32_e32 v2, vcc, 0x1eb89000, v102
	s_getreg_b32 s4, hwreg(HW_REG_XCC_ID, 0, 4)
	s_nop 0
	v_addc_co_u32_e32 v3, vcc, 0, v103, vcc
	v_add_co_u32_e32 v238, vcc, 0x1eb8a000, v102
	s_nop 1
	v_addc_co_u32_e32 v239, vcc, 0, v103, vcc
	global_load_dword v222, v[2:3], off offset:1024 sc1
	global_load_dword v223, v[2:3], off offset:1280 sc1
	global_load_dword v224, v[2:3], off offset:1536 sc1
	global_load_dword v225, v[2:3], off offset:1792 sc1
	global_load_dword v226, v[2:3], off offset:2048 sc1
	global_load_dword v227, v[2:3], off offset:2304 sc1
	global_load_dword v228, v[2:3], off offset:2560 sc1
	global_load_dword v229, v[2:3], off offset:2816 sc1
	global_load_dword v230, v[2:3], off offset:3072 sc1
	global_load_dword v231, v[2:3], off offset:3328 sc1
	global_load_dword v232, v[2:3], off offset:3584 sc1
	global_load_dword v233, v[2:3], off offset:3840 sc1
	global_load_dword v234, v[238:239], off sc1
	global_load_dword v235, v[238:239], off offset:256 sc1
	global_load_dword v236, v[238:239], off offset:512 sc1
	global_load_dword v237, v[238:239], off offset:768 sc1
	s_waitcnt vmcnt(0)
	v_mov_b32_e32 v0, v222
	v_mov_b32_e32 v4, v223
	v_mov_b32_e32 v6, v224
	s_and_b32 s7, s4, 15
	s_cmp_lg_u32 s7, 0
	s_cselect_b64 s[4:5], -1, 0
	s_mov_b32 s6, 0
	s_mov_b32 s37, 0
	s_waitcnt vmcnt(0) lgkmcnt(0)
	v_cmp_ne_u32_e32 vcc, 0, v0
	s_and_b64 s[4:5], vcc, s[4:5]
	s_cmp_gt_u32 s7, 1
	v_cndmask_b32_e64 v0, 0, 1, s[4:5]
	v_cmp_ne_u32_e64 s[4:5], 0, v4
	s_cselect_b64 s[8:9], -1, 0
	s_nop 0
	v_cndmask_b32_e64 v4, 0, 1, s[4:5]
	s_and_b64 s[4:5], s[4:5], s[8:9]
	v_addc_co_u32_e32 v4, vcc, 0, v4, vcc
	s_cmp_gt_u32 s7, 2
	v_cndmask_b32_e64 v5, 0, 1, s[4:5]
	v_cmp_ne_u32_e32 vcc, 0, v6
	s_cselect_b64 s[4:5], -1, 0
	s_nop 0
	v_cndmask_b32_e64 v6, 0, 1, vcc
	s_and_b64 vcc, vcc, s[4:5]
	v_addc_co_u32_e32 v0, vcc, v0, v5, vcc
	v_mov_b32_e32 v5, v225
	s_cmp_gt_u32 s7, 3
	s_cselect_b64 s[8:9], -1, 0
	s_waitcnt vmcnt(0) lgkmcnt(0)
	v_cmp_ne_u32_e32 vcc, 0, v5
	s_nop 1
	v_addc_co_u32_e64 v4, s[4:5], v4, v6, vcc
	v_mov_b32_e32 v6, v226
	s_and_b64 s[4:5], vcc, s[8:9]
	s_cmp_gt_u32 s7, 4
	v_cndmask_b32_e64 v5, 0, 1, s[4:5]
	s_cselect_b64 s[4:5], -1, 0
	s_waitcnt vmcnt(0) lgkmcnt(0)
	v_cmp_ne_u32_e32 vcc, 0, v6
	s_nop 1
	v_cndmask_b32_e64 v6, 0, 1, vcc
	s_and_b64 vcc, vcc, s[4:5]
	v_addc_co_u32_e32 v0, vcc, v0, v5, vcc
	v_mov_b32_e32 v5, v227
	s_cmp_gt_u32 s7, 5
	s_cselect_b64 s[8:9], -1, 0
	s_waitcnt vmcnt(0) lgkmcnt(0)
	v_cmp_ne_u32_e32 vcc, 0, v5
	s_nop 1
	v_addc_co_u32_e64 v4, s[4:5], v4, v6, vcc
	v_mov_b32_e32 v6, v228
	s_and_b64 s[4:5], vcc, s[8:9]
	s_cmp_gt_u32 s7, 6
	v_cndmask_b32_e64 v5, 0, 1, s[4:5]
	s_cselect_b64 s[4:5], -1, 0
	s_waitcnt vmcnt(0) lgkmcnt(0)
	v_cmp_ne_u32_e32 vcc, 0, v6
	s_nop 1
	v_cndmask_b32_e64 v6, 0, 1, vcc
	s_and_b64 vcc, vcc, s[4:5]
	v_addc_co_u32_e32 v0, vcc, v0, v5, vcc
	v_mov_b32_e32 v5, v229
	s_cmp_gt_u32 s7, 7
	s_cselect_b64 s[8:9], -1, 0
	s_waitcnt vmcnt(0) lgkmcnt(0)
	v_cmp_ne_u32_e32 vcc, 0, v5
	s_nop 1
	v_addc_co_u32_e64 v4, s[4:5], v4, v6, vcc
	v_mov_b32_e32 v6, v230
	s_and_b64 s[4:5], vcc, s[8:9]
	s_cmp_gt_u32 s7, 8
	v_cndmask_b32_e64 v5, 0, 1, s[4:5]
	s_cselect_b64 s[4:5], -1, 0
	s_waitcnt vmcnt(0) lgkmcnt(0)
	v_cmp_ne_u32_e32 vcc, 0, v6
	s_nop 1
	v_cndmask_b32_e64 v6, 0, 1, vcc
	s_and_b64 vcc, vcc, s[4:5]
	v_addc_co_u32_e32 v0, vcc, v0, v5, vcc
	v_mov_b32_e32 v5, v231
	s_cmp_gt_u32 s7, 9
	s_cselect_b64 s[8:9], -1, 0
	s_waitcnt vmcnt(0) lgkmcnt(0)
	v_cmp_ne_u32_e32 vcc, 0, v5
	s_nop 1
	v_addc_co_u32_e64 v4, s[4:5], v4, v6, vcc
	v_mov_b32_e32 v6, v232
	s_and_b64 s[4:5], vcc, s[8:9]
	v_mov_b32_e32 v2, v233
	s_cmp_gt_u32 s7, 10
	v_cndmask_b32_e64 v5, 0, 1, s[4:5]
	s_cselect_b64 s[4:5], -1, 0
	s_waitcnt vmcnt(0) lgkmcnt(0)
	v_cmp_ne_u32_e32 vcc, 0, v6
	s_nop 1
	v_cndmask_b32_e64 v6, 0, 1, vcc
	s_and_b64 vcc, vcc, s[4:5]
	v_addc_co_u32_e32 v0, vcc, v0, v5, vcc
	v_cmp_ne_u32_e32 vcc, 0, v2
	s_cmp_gt_u32 s7, 11
	s_cselect_b64 s[8:9], -1, 0
	v_addc_co_u32_e64 v4, s[4:5], v4, v6, vcc
	s_and_b64 s[4:5], vcc, s[8:9]
	s_nop 0
	v_cndmask_b32_e64 v5, 0, 1, s[4:5]
	s_mov_b32 s4, 0x1eb8a000
	v_add_co_u32_e32 v2, vcc, s4, v102
	s_cmp_gt_u32 s7, 12
	s_nop 0
	v_addc_co_u32_e32 v3, vcc, 0, v103, vcc
	v_mov_b32_e32 v6, v234
	s_cselect_b64 s[4:5], -1, 0
	s_waitcnt vmcnt(0) lgkmcnt(0)
	v_cmp_ne_u32_e32 vcc, 0, v6
	s_nop 1
	v_cndmask_b32_e64 v6, 0, 1, vcc
	s_and_b64 vcc, vcc, s[4:5]
	v_addc_co_u32_e32 v0, vcc, v0, v5, vcc
	v_mov_b32_e32 v5, v235
	s_cmp_gt_u32 s7, 13
	s_cselect_b64 s[8:9], -1, 0
	s_waitcnt vmcnt(0) lgkmcnt(0)
	v_cmp_ne_u32_e32 vcc, 0, v5
	s_nop 1
	v_addc_co_u32_e64 v4, s[4:5], v4, v6, vcc
	v_mov_b32_e32 v6, v236
	s_and_b64 s[4:5], vcc, s[8:9]
	v_mov_b32_e32 v2, v237
	s_cmp_eq_u32 s7, 15
	v_cndmask_b32_e64 v5, 0, 1, s[4:5]
	s_cselect_b64 s[4:5], -1, 0
	s_waitcnt vmcnt(0) lgkmcnt(0)
	v_cmp_ne_u32_e32 vcc, 0, v6
	s_nop 1
	v_cndmask_b32_e64 v6, 0, 1, vcc
	s_and_b64 vcc, vcc, s[4:5]
	v_addc_co_u32_e32 v0, vcc, v0, v5, vcc
	v_cmp_ne_u32_e32 vcc, 0, v2
	v_readfirstlane_b32 s80, v0
	s_nop 0
	v_addc_co_u32_e32 v2, vcc, v4, v6, vcc
	s_nop 0
	v_readfirstlane_b32 s4, v2
	s_max_u32 s36, s4, 1
	v_cvt_f32_u32_e32 v0, s36
	s_cmp_gt_u32 s80, 15
	v_rcp_iflag_f32_e32 v0, v0
	s_cbranch_scc1 .LBB0_434
	v_mul_f32_e32 v2, 0x4f7ffffe, v0
	v_cvt_u32_f32_e32 v2, v2
	s_sub_i32 s5, 0, s36
	s_sub_i32 s4, s36, s80
	s_add_i32 s4, s4, 15
	v_readfirstlane_b32 s7, v2
	s_mul_i32 s5, s5, s7
	s_mul_hi_u32 s5, s7, s5
	s_add_i32 s7, s7, s5
	s_mul_hi_u32 s5, s4, s7
	s_mul_i32 s7, s5, s36
	s_sub_i32 s4, s4, s7
	s_add_i32 s7, s5, 1
	s_sub_i32 s8, s4, s36
	s_cmp_ge_u32 s4, s36
	s_cselect_b32 s5, s7, s5
	s_cselect_b32 s4, s8, s4
	s_add_i32 s7, s5, 1
	s_cmp_ge_u32 s4, s36
	s_cselect_b32 s37, s7, s5
